# swa key tiles fully inside the window skip the mask and pair the bias lookups
# speedup vs baseline: 1.0283x; 1.0194x over previous
.LBB0_490:
	v_add_u32_e32 v32, v92, v82
	ds_read_b128 v[32:35], v32
	v_add_u32_e32 v36, v92, v83
	ds_read_b128 v[98:101], v36
	v_add_u32_e32 v97, v92, v84
	s_waitcnt vmcnt(3) lgkmcnt(1)
	v_mfma_f32_32x32x16_bf16 v[32:47], v[32:35], v[48:51], 0
	s_waitcnt vmcnt(2) lgkmcnt(0)
	v_mfma_f32_32x32x16_bf16 v[32:47], v[98:101], v[52:55], v[32:47]
	ds_read_b128 v[98:101], v97
	v_add_u32_e32 v97, v92, v86
	ds_read_b128 v[102:105], v97
	v_mov_b32_e32 v97, 0xff800000
	s_waitcnt vmcnt(1) lgkmcnt(1)
	v_mfma_f32_32x32x16_bf16 v[32:47], v[98:101], v[56:59], v[32:47]
	v_add_u32_e32 v99, s48, v94
	v_add_u32_e32 v100, 27, v95
	v_cmp_lt_u32_e32 vcc, s43, v100
	v_cmp_le_u32_e64 s[0:1], s47, v99
	s_and_b64 s[50:51], vcc, s[0:1]
	v_mov_b32_e32 v98, 0xff800000
	s_waitcnt vmcnt(0) lgkmcnt(0)
	v_mfma_f32_32x32x16_bf16 v[32:47], v[102:105], v[60:63], v[32:47]
	v_readfirstlane_b32 s0, v99
	s_cmp_lt_u32 s0, s47
	s_cbranch_scc1 .Lswa_sc_slow
	s_cmp_eq_u32 s48, 0
	s_cbranch_scc1 .Lswa_sc_slow
	s_cmpk_eq_u32 s48, 0x80
	s_cbranch_scc1 .Lswa_sc_slow
	v_add_u32_e32 v180, 26, v95
	v_and_b32_e32 v180, 0x7f, v180
	v_lshl_add_u32 v180, v180, 2, v93
	ds_read2_b32 v[196:197], v180 offset1:1
	v_add_u32_e32 v182, 24, v95
	v_and_b32_e32 v182, 0x7f, v182
	v_lshl_add_u32 v182, v182, 2, v93
	ds_read2_b32 v[198:199], v182 offset1:1
	v_add_u32_e32 v184, 18, v95
	v_and_b32_e32 v184, 0x7f, v184
	v_lshl_add_u32 v184, v184, 2, v93
	ds_read2_b32 v[200:201], v184 offset1:1
	v_add_u32_e32 v186, 16, v95
	v_and_b32_e32 v186, 0x7f, v186
	v_lshl_add_u32 v186, v186, 2, v93
	ds_read2_b32 v[202:203], v186 offset1:1
	v_add_u32_e32 v188, 10, v95
	v_and_b32_e32 v188, 0x7f, v188
	v_lshl_add_u32 v188, v188, 2, v93
	ds_read2_b32 v[204:205], v188 offset1:1
	v_add_u32_e32 v190, 8, v95
	v_and_b32_e32 v190, 0x7f, v190
	v_lshl_add_u32 v190, v190, 2, v93
	ds_read2_b32 v[206:207], v190 offset1:1
	v_add_u32_e32 v192, 2, v95
	v_and_b32_e32 v192, 0x7f, v192
	v_lshl_add_u32 v192, v192, 2, v93
	ds_read2_b32 v[208:209], v192 offset1:1
	v_mov_b32_e32 v194, v95
	v_and_b32_e32 v194, 0x7f, v194
	v_lshl_add_u32 v194, v194, 2, v93
	ds_read2_b32 v[210:211], v194 offset1:1
	s_waitcnt lgkmcnt(0)
	v_fmamk_f32 v98, v32, 0x3e000000, v197
	v_fmamk_f32 v97, v33, 0x3e000000, v196
	v_fmamk_f32 v33, v34, 0x3e000000, v199
	v_fmamk_f32 v32, v35, 0x3e000000, v198
	v_fmamk_f32 v35, v36, 0x3e000000, v201
	v_fmamk_f32 v34, v37, 0x3e000000, v200
	v_fmamk_f32 v37, v38, 0x3e000000, v203
	v_fmamk_f32 v36, v39, 0x3e000000, v202
	v_fmamk_f32 v100, v40, 0x3e000000, v205
	v_fmamk_f32 v39, v41, 0x3e000000, v204
	v_fmamk_f32 v41, v42, 0x3e000000, v207
	v_fmamk_f32 v40, v43, 0x3e000000, v206
	v_fmamk_f32 v43, v44, 0x3e000000, v209
	v_fmamk_f32 v42, v45, 0x3e000000, v208
	v_fmamk_f32 v45, v46, 0x3e000000, v211
	v_fmamk_f32 v44, v47, 0x3e000000, v210
	s_branch .Lswa_sc_done
.Lswa_sc_slow:
	v_add_u32_e32 v180, 27, v95
	v_and_b32_e32 v196, 0x7f, v180
	v_lshl_add_u32 v196, v196, 2, v93
	ds_read_b32 v196, v196
	v_add_u32_e32 v181, 26, v95
	v_and_b32_e32 v197, 0x7f, v181
	v_lshl_add_u32 v197, v197, 2, v93
	ds_read_b32 v197, v197
	v_add_u32_e32 v182, 25, v95
	v_and_b32_e32 v198, 0x7f, v182
	v_lshl_add_u32 v198, v198, 2, v93
	ds_read_b32 v198, v198
	v_add_u32_e32 v183, 24, v95
	v_and_b32_e32 v199, 0x7f, v183
	v_lshl_add_u32 v199, v199, 2, v93
	ds_read_b32 v199, v199
	v_add_u32_e32 v184, 19, v95
	v_and_b32_e32 v200, 0x7f, v184
	v_lshl_add_u32 v200, v200, 2, v93
	ds_read_b32 v200, v200
	v_add_u32_e32 v185, 18, v95
	v_and_b32_e32 v201, 0x7f, v185
	v_lshl_add_u32 v201, v201, 2, v93
	ds_read_b32 v201, v201
	v_add_u32_e32 v186, 17, v95
	v_and_b32_e32 v202, 0x7f, v186
	v_lshl_add_u32 v202, v202, 2, v93
	ds_read_b32 v202, v202
	v_add_u32_e32 v187, 16, v95
	v_and_b32_e32 v203, 0x7f, v187
	v_lshl_add_u32 v203, v203, 2, v93
	ds_read_b32 v203, v203
	v_add_u32_e32 v188, 11, v95
	v_and_b32_e32 v204, 0x7f, v188
	v_lshl_add_u32 v204, v204, 2, v93
	ds_read_b32 v204, v204
	v_add_u32_e32 v189, 10, v95
	v_and_b32_e32 v205, 0x7f, v189
	v_lshl_add_u32 v205, v205, 2, v93
	ds_read_b32 v205, v205
	v_add_u32_e32 v190, 9, v95
	v_and_b32_e32 v206, 0x7f, v190
	v_lshl_add_u32 v206, v206, 2, v93
	ds_read_b32 v206, v206
	v_add_u32_e32 v191, 8, v95
	v_and_b32_e32 v207, 0x7f, v191
	v_lshl_add_u32 v207, v207, 2, v93
	ds_read_b32 v207, v207
	v_add_u32_e32 v192, 3, v95
	v_and_b32_e32 v208, 0x7f, v192
	v_lshl_add_u32 v208, v208, 2, v93
	ds_read_b32 v208, v208
	v_add_u32_e32 v193, 2, v95
	v_and_b32_e32 v209, 0x7f, v193
	v_lshl_add_u32 v209, v209, 2, v93
	ds_read_b32 v209, v209
	v_add_u32_e32 v194, 1, v95
	v_and_b32_e32 v210, 0x7f, v194
	v_lshl_add_u32 v210, v210, 2, v93
	ds_read_b32 v210, v210
	v_mov_b32_e32 v195, v95
	v_and_b32_e32 v211, 0x7f, v195
	v_lshl_add_u32 v211, v211, 2, v93
	ds_read_b32 v211, v211
	s_waitcnt lgkmcnt(0)
	v_fmac_f32_e32 v196, 0x3e000000, v32
	v_fmac_f32_e32 v197, 0x3e000000, v33
	v_fmac_f32_e32 v198, 0x3e000000, v34
	v_fmac_f32_e32 v199, 0x3e000000, v35
	v_fmac_f32_e32 v200, 0x3e000000, v36
	v_fmac_f32_e32 v201, 0x3e000000, v37
	v_fmac_f32_e32 v202, 0x3e000000, v38
	v_fmac_f32_e32 v203, 0x3e000000, v39
	v_fmac_f32_e32 v204, 0x3e000000, v40
	v_fmac_f32_e32 v205, 0x3e000000, v41
	v_fmac_f32_e32 v206, 0x3e000000, v42
	v_fmac_f32_e32 v207, 0x3e000000, v43
	v_fmac_f32_e32 v208, 0x3e000000, v44
	v_fmac_f32_e32 v209, 0x3e000000, v45
	v_fmac_f32_e32 v210, 0x3e000000, v46
	v_fmac_f32_e32 v211, 0x3e000000, v47
	v_mov_b32_e32 v212, 0xff800000
	v_cmp_lt_u32_e32 vcc, s43, v180
	v_cmp_le_u32_e64 s[0:1], s47, v99
	s_and_b64 vcc, vcc, s[0:1]
	v_cndmask_b32_e32 v98, v212, v196, vcc
	v_add_u32_e32 v213, 1, v99
	v_cmp_lt_u32_e32 vcc, s43, v181
	v_cmp_le_u32_e64 s[0:1], s47, v213
	s_and_b64 vcc, vcc, s[0:1]
	v_cndmask_b32_e32 v97, v212, v197, vcc
	v_add_u32_e32 v213, 2, v99
	v_cmp_lt_u32_e32 vcc, s43, v182
	v_cmp_le_u32_e64 s[0:1], s47, v213
	s_and_b64 vcc, vcc, s[0:1]
	v_cndmask_b32_e32 v33, v212, v198, vcc
	v_add_u32_e32 v213, 3, v99
	v_cmp_lt_u32_e32 vcc, s43, v183
	v_cmp_le_u32_e64 s[0:1], s47, v213
	s_and_b64 vcc, vcc, s[0:1]
	v_cndmask_b32_e32 v32, v212, v199, vcc
	v_add_u32_e32 v213, 8, v99
	v_cmp_lt_u32_e32 vcc, s43, v184
	v_cmp_le_u32_e64 s[0:1], s47, v213
	s_and_b64 vcc, vcc, s[0:1]
	v_cndmask_b32_e32 v35, v212, v200, vcc
	v_add_u32_e32 v213, 9, v99
	v_cmp_lt_u32_e32 vcc, s43, v185
	v_cmp_le_u32_e64 s[0:1], s47, v213
	s_and_b64 vcc, vcc, s[0:1]
	v_cndmask_b32_e32 v34, v212, v201, vcc
	v_add_u32_e32 v213, 10, v99
	v_cmp_lt_u32_e32 vcc, s43, v186
	v_cmp_le_u32_e64 s[0:1], s47, v213
	s_and_b64 vcc, vcc, s[0:1]
	v_cndmask_b32_e32 v37, v212, v202, vcc
	v_add_u32_e32 v213, 11, v99
	v_cmp_lt_u32_e32 vcc, s43, v187
	v_cmp_le_u32_e64 s[0:1], s47, v213
	s_and_b64 vcc, vcc, s[0:1]
	v_cndmask_b32_e32 v36, v212, v203, vcc
	v_add_u32_e32 v213, 16, v99
	v_cmp_lt_u32_e32 vcc, s43, v188
	v_cmp_le_u32_e64 s[0:1], s47, v213
	s_and_b64 vcc, vcc, s[0:1]
	v_cndmask_b32_e32 v100, v212, v204, vcc
	v_add_u32_e32 v213, 17, v99
	v_cmp_lt_u32_e32 vcc, s43, v189
	v_cmp_le_u32_e64 s[0:1], s47, v213
	s_and_b64 vcc, vcc, s[0:1]
	v_cndmask_b32_e32 v39, v212, v205, vcc
	v_add_u32_e32 v213, 18, v99
	v_cmp_lt_u32_e32 vcc, s43, v190
	v_cmp_le_u32_e64 s[0:1], s47, v213
	s_and_b64 vcc, vcc, s[0:1]
	v_cndmask_b32_e32 v41, v212, v206, vcc
	v_add_u32_e32 v213, 19, v99
	v_cmp_lt_u32_e32 vcc, s43, v191
	v_cmp_le_u32_e64 s[0:1], s47, v213
	s_and_b64 vcc, vcc, s[0:1]
	v_cndmask_b32_e32 v40, v212, v207, vcc
	v_add_u32_e32 v213, 24, v99
	v_cmp_lt_u32_e32 vcc, s43, v192
	v_cmp_le_u32_e64 s[0:1], s47, v213
	s_and_b64 vcc, vcc, s[0:1]
	v_cndmask_b32_e32 v43, v212, v208, vcc
	v_add_u32_e32 v213, 25, v99
	v_cmp_lt_u32_e32 vcc, s43, v193
	v_cmp_le_u32_e64 s[0:1], s47, v213
	s_and_b64 vcc, vcc, s[0:1]
	v_cndmask_b32_e32 v42, v212, v209, vcc
	v_add_u32_e32 v213, 26, v99
	v_cmp_lt_u32_e32 vcc, s43, v194
	v_cmp_le_u32_e64 s[0:1], s47, v213
	s_and_b64 vcc, vcc, s[0:1]
	v_cndmask_b32_e32 v45, v212, v210, vcc
	v_add_u32_e32 v213, 27, v99
	v_cmp_lt_u32_e32 vcc, s43, v195
	v_cmp_le_u32_e64 s[0:1], s47, v213
	s_and_b64 vcc, vcc, s[0:1]
	v_cndmask_b32_e32 v44, v212, v211, vcc
.Lswa_sc_done:
	v_max3_f32 v38, v98, s33, v97
	v_max3_f32 v38, v38, v33, v32
	v_max3_f32 v38, v38, v35, v34
	v_max3_f32 v38, v38, v37, v36
	v_max3_f32 v38, v38, v100, v39
	v_max3_f32 v38, v38, v41, v40
	v_max3_f32 v38, v38, v43, v42
	v_max3_f32 v38, v38, v45, v44
	ds_bpermute_b32 v46, v80, v38
	s_add_i32 s48, s48, 32
	v_subrev_u32_e32 v95, 32, v95
	s_cmpk_lg_i32 s48, 0xa0
	v_add_u32_e32 v92, 0x1000, v92
	s_waitcnt lgkmcnt(0)
	v_max3_f32 v38, v96, v38, v46
	v_sub_f32_e32 v32, v32, v38
	v_mul_f32_e32 v32, 0x3fb8aa3b, v32
	v_exp_f32_e32 v105, v32
	v_sub_f32_e32 v32, v35, v38
	v_mul_f32_e32 v32, 0x3fb8aa3b, v32
	v_exp_f32_e32 v106, v32
	v_sub_f32_e32 v32, v34, v38
	v_mul_f32_e32 v32, 0x3fb8aa3b, v32
	v_exp_f32_e32 v107, v32
	v_sub_f32_e32 v32, v37, v38
	v_mul_f32_e32 v32, 0x3fb8aa3b, v32
	v_exp_f32_e32 v37, v32
	v_sub_f32_e32 v32, v36, v38
	v_mul_f32_e32 v32, 0x3fb8aa3b, v32
	v_exp_f32_e32 v36, v32
	v_sub_f32_e32 v32, v100, v38
	v_mul_f32_e32 v32, 0x3fb8aa3b, v32
	v_exp_f32_e32 v100, v32
	v_sub_f32_e32 v32, v39, v38
	v_mul_f32_e32 v32, 0x3fb8aa3b, v32
	v_exp_f32_e32 v39, v32
	v_sub_f32_e32 v32, v41, v38
	v_mul_f32_e32 v32, 0x3fb8aa3b, v32
	v_exp_f32_e32 v108, v32
	v_sub_f32_e32 v32, v40, v38
	v_mul_f32_e32 v32, 0x3fb8aa3b, v32
	v_sub_f32_e32 v46, v96, v38
	v_exp_f32_e32 v109, v32
	v_sub_f32_e32 v32, v43, v38
	v_mul_f32_e32 v46, 0x3fb8aa3b, v46
	v_mul_f32_e32 v32, 0x3fb8aa3b, v32
	v_exp_f32_e32 v102, v46
	v_sub_f32_e32 v46, v98, v38
	v_exp_f32_e32 v110, v32
	v_sub_f32_e32 v32, v42, v38
	v_add_u32_e32 v34, -6, v91
	v_mul_f32_e32 v46, 0x3fb8aa3b, v46
	v_mul_f32_e32 v32, 0x3fb8aa3b, v32
	v_xor_b32_e32 v34, v34, v74
	v_add_u32_e32 v35, -4, v91
	v_exp_f32_e32 v101, v46
	v_sub_f32_e32 v46, v97, v38
	v_exp_f32_e32 v111, v32
	v_sub_f32_e32 v32, v45, v38
	v_xor_b32_e32 v35, v35, v74
	v_lshl_add_u32 v34, v34, 3, v81
	v_mul_f32_e32 v46, 0x3fb8aa3b, v46
	v_mul_f32_e32 v32, 0x3fb8aa3b, v32
	ds_read2st64_b64 v[40:43], v34 offset0:64 offset1:96
	v_lshl_add_u32 v34, v35, 3, v81
	v_pk_mul_f32 v[14:15], v[14:15], v[102:103] op_sel_hi:[1,0]
	v_pk_mul_f32 v[12:13], v[12:13], v[102:103] op_sel_hi:[1,0]
	v_pk_mul_f32 v[10:11], v[10:11], v[102:103] op_sel_hi:[1,0]
	v_pk_mul_f32 v[8:9], v[8:9], v[102:103] op_sel_hi:[1,0]
	v_pk_mul_f32 v[6:7], v[6:7], v[102:103] op_sel_hi:[1,0]
	v_pk_mul_f32 v[4:5], v[4:5], v[102:103] op_sel_hi:[1,0]
	v_pk_mul_f32 v[2:3], v[2:3], v[102:103] op_sel_hi:[1,0]
	v_pk_mul_f32 v[0:1], v[0:1], v[102:103] op_sel_hi:[1,0]
	v_exp_f32_e32 v103, v46
	v_exp_f32_e32 v112, v32
	v_sub_f32_e32 v32, v44, v38
	ds_read2st64_b64 v[44:47], v34 offset0:64 offset1:96
	s_waitcnt lgkmcnt(1)
	v_mov_b32_e32 v96, v40
	v_mov_b32_e32 v97, v41
	v_sub_f32_e32 v33, v33, v38
	v_mul_f32_e32 v33, 0x3fb8aa3b, v33
	s_waitcnt lgkmcnt(0)
	v_mov_b32_e32 v98, v44
	v_mov_b32_e32 v99, v45
	v_pk_mul_f32 v[30:31], v[30:31], v[102:103] op_sel_hi:[1,0]
	v_pk_mul_f32 v[28:29], v[28:29], v[102:103] op_sel_hi:[1,0]
	v_pk_mul_f32 v[26:27], v[26:27], v[102:103] op_sel_hi:[1,0]
	v_pk_mul_f32 v[24:25], v[24:25], v[102:103] op_sel_hi:[1,0]
	v_pk_mul_f32 v[22:23], v[22:23], v[102:103] op_sel_hi:[1,0]
	v_pk_mul_f32 v[20:21], v[20:21], v[102:103] op_sel_hi:[1,0]
	v_pk_mul_f32 v[18:19], v[18:19], v[102:103] op_sel_hi:[1,0]
	v_pk_mul_f32 v[16:17], v[16:17], v[102:103] op_sel_hi:[1,0]
	v_add_u32_e32 v40, -2, v91
	v_exp_f32_e32 v104, v33
	v_mul_f32_e32 v113, 0x3fb8aa3b, v32
	v_cvt_pk_bf16_f32 v32, v101, v103
	v_cvt_pk_bf16_f32 v33, v104, v105
	v_cvt_pk_bf16_f32 v34, v106, v107
	v_cvt_pk_bf16_f32 v35, v37, v36
	v_xor_b32_e32 v40, v40, v74
	v_mfma_f32_32x32x16_bf16 v[16:31], v[96:99], v[32:35], v[16:31]
	v_xor_b32_e32 v96, v91, v74
	v_lshl_add_u32 v40, v40, 3, v81
	v_lshl_add_u32 v96, v96, 3, v81
	v_mov_b32_e32 v44, v42
	v_mov_b32_e32 v45, v43
	ds_read2st64_b64 v[40:43], v40 offset0:64 offset1:96
	ds_read2st64_b64 v[96:99], v96 offset0:64 offset1:96
	v_mfma_f32_32x32x16_bf16 v[0:15], v[44:47], v[32:35], v[0:15]
	s_waitcnt lgkmcnt(1)
	v_mov_b32_e32 v32, v40
	v_mov_b32_e32 v33, v41
	s_waitcnt lgkmcnt(0)
	v_mov_b32_e32 v34, v96
	v_mov_b32_e32 v35, v97
	v_fmac_f32_e32 v101, v65, v102
	v_exp_f32_e32 v113, v113
	v_cvt_pk_bf16_f32 v44, v100, v39
	v_cvt_pk_bf16_f32 v45, v108, v109
	v_cvt_pk_bf16_f32 v46, v110, v111
	v_cvt_pk_bf16_f32 v47, v112, v113
	v_mov_b32_e32 v96, v42
	v_mfma_f32_32x32x16_bf16 v[16:31], v[32:35], v[44:47], v[16:31]
	v_add_f32_e32 v32, v103, v101
	v_add_f32_e32 v32, v104, v32
	v_mov_b32_e32 v97, v43
	v_add_f32_e32 v32, v105, v32
	v_add_f32_e32 v32, v106, v32
	v_add_f32_e32 v32, v107, v32
	v_add_f32_e32 v32, v37, v32
	v_add_f32_e32 v32, v36, v32
	v_mfma_f32_32x32x16_bf16 v[0:15], v[96:99], v[44:47], v[0:15]
	v_add_f32_e32 v32, v100, v32
	v_add_f32_e32 v32, v39, v32
	v_add_f32_e32 v32, v108, v32
	v_add_f32_e32 v32, v109, v32
	v_add_f32_e32 v32, v110, v32
	v_add_f32_e32 v32, v111, v32
	v_add_f32_e32 v32, v112, v32
	v_add_f32_e32 v65, v113, v32
	v_add_u32_e32 v91, 8, v91
	s_cbranch_scc0 .LBB0_486
	v_mov_b32_e32 v96, v38
	s_branch .LBB0_490
